# plus: residual epilogues (phases 6, 11) transpose each wave tile through a wave-private LDS image so every global load/store instruction covers full 256-B row segments
# speedup vs baseline: 1.0086x; 1.0086x over previous
;   DI void operator()(const f32x16 (&acc)[2][4], int mbase, int nbase, int l32, int g) const {
; #pragma unroll
;     for (int nb = 0; nb < 2; ++nb)
; #pragma unroll
;       for (int mb = 0; mb < 4; ++mb) {
;         const size_t tok = mbase + 32 * mb + l32;
; #pragma unroll
;         for (int j = 0; j < 4; ++j) {
;           const int n = nbase + 32 * nb + 8 * j + 4 * g;
;           f32x4 r = *(const f32x4*)(R + tok * D + n);
;           r[0] += acc[nb][mb][4 * j]; r[1] += acc[nb][mb][4 * j + 1]; r[2] += acc[nb][mb][4 * j + 2]; r[3] += acc[nb][mb][4 * j + 3];
;           *(f32x4*)(O + tok * D + n) = r;
;         }
;       }
;   }
; DI void phase_gemm_out(const Params& p, char* smem, const bf16_t* Wt, const float* R, float* O) {
;     ...
;     WAVE_GEOM;
;     f32x16 acc[2][4];
;     gemm_core<false>(tl, nx, has_next, has_next, pre, ra, rb, smem, acc);
;     const float* Rq = R; asm volatile("" : "+s"(Rq));
;     EpiResid e{Rq, O};
;     e(acc, mt * 256 + wm_ * 128, nt * 256 + wn_ * 64, l32_, g_);
.LBB0_744:
	s_lshr_b32 s98, s11, 6
	s_and_b32 s12, s11, 0xc0
	s_ashr_i32 s11, s11, 1
	s_and_b32 s11, s11, 0xffffff80
	s_add_i32 s11, s11, s39
	s_mul_i32 s98, s98, 0x2200
	s_add_i32 s98, s98, 0x12010
	s_or_b32 s99, s12, s10
	s_mov_b64 s[2:3], s[68:69]
	s_mov_b64 s[100:101], s[20:21]
	s_add_i32 s26, s26, s27
	s_add_i32 s28, s28, s29
	s_mov_b64 s[12:13], -1
	s_barrier
	v_and_b32_e32 v239, 31, v190
	v_bfe_u32 v240, v190, 5, 1
	v_mul_u32_u24_e32 v236, 0x110, v239
	v_lshl_add_u32 v236, v240, 4, v236
	v_add_u32_e32 v236, s98, v236
	v_and_b32_e32 v239, 15, v190
	v_bfe_u32 v240, v190, 4, 2
	v_mul_u32_u24_e32 v237, 0x110, v240
	v_lshl_add_u32 v237, v239, 4, v237
	v_add_u32_e32 v237, s98, v237
	v_add_u32_e32 v238, s11, v240
	v_lshlrev_b32_e32 v238, 13, v238
	v_lshl_add_u32 v240, v239, 2, s99
	v_lshl_add_u32 v238, v240, 2, v238
	global_load_dwordx4 v[160:163], v238, s[2:3]
	s_add_u32 s2, s2, 0x8000
	s_addc_u32 s3, s3, 0
	global_load_dwordx4 v[164:167], v238, s[2:3]
	s_add_u32 s2, s2, 0x8000
	s_addc_u32 s3, s3, 0
	global_load_dwordx4 v[168:171], v238, s[2:3]
	s_add_u32 s2, s2, 0x8000
	s_addc_u32 s3, s3, 0
	global_load_dwordx4 v[172:175], v238, s[2:3]
	s_add_u32 s2, s2, 0x8000
	s_addc_u32 s3, s3, 0
	global_load_dwordx4 v[176:179], v238, s[2:3]
	s_add_u32 s2, s2, 0x8000
	s_addc_u32 s3, s3, 0
	global_load_dwordx4 v[180:183], v238, s[2:3]
	s_add_u32 s2, s2, 0x8000
	s_addc_u32 s3, s3, 0
	global_load_dwordx4 v[186:189], v238, s[2:3]
	s_add_u32 s2, s2, 0x8000
	s_addc_u32 s3, s3, 0
	global_load_dwordx4 v[192:195], v238, s[2:3]
	s_add_u32 s2, s2, 0x8000
	s_addc_u32 s3, s3, 0
	global_load_dwordx4 v[200:203], v238, s[2:3]
	s_add_u32 s2, s2, 0x8000
	s_addc_u32 s3, s3, 0
	global_load_dwordx4 v[208:211], v238, s[2:3]
	s_add_u32 s2, s2, 0x8000
	s_addc_u32 s3, s3, 0
	global_load_dwordx4 v[212:215], v238, s[2:3]
	s_add_u32 s2, s2, 0x8000
	s_addc_u32 s3, s3, 0
	global_load_dwordx4 v[216:219], v238, s[2:3]
	s_add_u32 s2, s2, 0x8000
	s_addc_u32 s3, s3, 0
	global_load_dwordx4 v[220:223], v238, s[2:3]
	s_add_u32 s2, s2, 0x8000
	s_addc_u32 s3, s3, 0
	global_load_dwordx4 v[224:227], v238, s[2:3]
	s_add_u32 s2, s2, 0x8000
	s_addc_u32 s3, s3, 0
	global_load_dwordx4 v[228:231], v238, s[2:3]
	s_add_u32 s2, s2, 0x8000
	s_addc_u32 s3, s3, 0
	global_load_dwordx4 v[232:235], v238, s[2:3]
	s_add_u32 s2, s2, 0x8000
	s_addc_u32 s3, s3, 0
	ds_write_b128 v236, v[112:115]
	ds_write_b128 v236, v[116:119] offset:32
	ds_write_b128 v236, v[120:123] offset:64
	ds_write_b128 v236, v[124:127] offset:96
	ds_write_b128 v236, v[48:51] offset:128
	ds_write_b128 v236, v[52:55] offset:160
	ds_write_b128 v236, v[56:59] offset:192
	ds_write_b128 v236, v[60:63] offset:224
	ds_read_b128 v[112:115], v237
	ds_read_b128 v[116:119], v237 offset:1088
	ds_read_b128 v[120:123], v237 offset:2176
	ds_read_b128 v[124:127], v237 offset:3264
	s_waitcnt lgkmcnt(0)
	s_waitcnt vmcnt(15)
	v_pk_add_f32 v[112:113], v[112:113], v[160:161]
	v_pk_add_f32 v[114:115], v[114:115], v[162:163]
	global_store_dwordx4 v238, v[112:115], s[100:101]
	s_add_u32 s100, s100, 0x8000
	s_addc_u32 s101, s101, 0
	s_waitcnt vmcnt(15)
	v_pk_add_f32 v[116:117], v[116:117], v[164:165]
	v_pk_add_f32 v[118:119], v[118:119], v[166:167]
	global_store_dwordx4 v238, v[116:119], s[100:101]
	s_add_u32 s100, s100, 0x8000
	s_addc_u32 s101, s101, 0
	s_waitcnt vmcnt(15)
	v_pk_add_f32 v[120:121], v[120:121], v[168:169]
	v_pk_add_f32 v[122:123], v[122:123], v[170:171]
	global_store_dwordx4 v238, v[120:123], s[100:101]
	s_add_u32 s100, s100, 0x8000
	s_addc_u32 s101, s101, 0
	s_waitcnt vmcnt(15)
	v_pk_add_f32 v[124:125], v[124:125], v[172:173]
	v_pk_add_f32 v[126:127], v[126:127], v[174:175]
	global_store_dwordx4 v238, v[124:127], s[100:101]
	s_add_u32 s100, s100, 0x8000
	s_addc_u32 s101, s101, 0
	global_load_dwordx4 v[160:163], v238, s[2:3]
	s_add_u32 s2, s2, 0x8000
	s_addc_u32 s3, s3, 0
	global_load_dwordx4 v[164:167], v238, s[2:3]
	s_add_u32 s2, s2, 0x8000
	s_addc_u32 s3, s3, 0
	global_load_dwordx4 v[168:171], v238, s[2:3]
	s_add_u32 s2, s2, 0x8000
	s_addc_u32 s3, s3, 0
	global_load_dwordx4 v[172:175], v238, s[2:3]
	s_add_u32 s2, s2, 0x8000
	s_addc_u32 s3, s3, 0
	ds_read_b128 v[48:51], v237 offset:4352
	ds_read_b128 v[52:55], v237 offset:5440
	ds_read_b128 v[56:59], v237 offset:6528
	ds_read_b128 v[60:63], v237 offset:7616
	s_waitcnt lgkmcnt(0)
	s_waitcnt vmcnt(19)
	v_pk_add_f32 v[48:49], v[48:49], v[176:177]
	v_pk_add_f32 v[50:51], v[50:51], v[178:179]
	global_store_dwordx4 v238, v[48:51], s[100:101]
	s_add_u32 s100, s100, 0x8000
	s_addc_u32 s101, s101, 0
	s_waitcnt vmcnt(19)
	v_pk_add_f32 v[52:53], v[52:53], v[180:181]
	v_pk_add_f32 v[54:55], v[54:55], v[182:183]
	global_store_dwordx4 v238, v[52:55], s[100:101]
	s_add_u32 s100, s100, 0x8000
	s_addc_u32 s101, s101, 0
	s_waitcnt vmcnt(19)
	v_pk_add_f32 v[56:57], v[56:57], v[186:187]
	v_pk_add_f32 v[58:59], v[58:59], v[188:189]
	global_store_dwordx4 v238, v[56:59], s[100:101]
	s_add_u32 s100, s100, 0x8000
	s_addc_u32 s101, s101, 0
	s_waitcnt vmcnt(19)
	v_pk_add_f32 v[60:61], v[60:61], v[192:193]
	v_pk_add_f32 v[62:63], v[62:63], v[194:195]
	global_store_dwordx4 v238, v[60:63], s[100:101]
	s_add_u32 s100, s100, 0x8000
	s_addc_u32 s101, s101, 0
	global_load_dwordx4 v[176:179], v238, s[2:3]
	s_add_u32 s2, s2, 0x8000
	s_addc_u32 s3, s3, 0
	global_load_dwordx4 v[180:183], v238, s[2:3]
	s_add_u32 s2, s2, 0x8000
	s_addc_u32 s3, s3, 0
	global_load_dwordx4 v[186:189], v238, s[2:3]
	s_add_u32 s2, s2, 0x8000
	s_addc_u32 s3, s3, 0
	global_load_dwordx4 v[192:195], v238, s[2:3]
	s_add_u32 s2, s2, 0x8000
	s_addc_u32 s3, s3, 0
	ds_write_b128 v236, v[96:99]
	ds_write_b128 v236, v[100:103] offset:32
	ds_write_b128 v236, v[104:107] offset:64
	ds_write_b128 v236, v[108:111] offset:96
	ds_write_b128 v236, v[32:35] offset:128
	ds_write_b128 v236, v[36:39] offset:160
	ds_write_b128 v236, v[40:43] offset:192
	ds_write_b128 v236, v[44:47] offset:224
	ds_read_b128 v[96:99], v237
	ds_read_b128 v[100:103], v237 offset:1088
	ds_read_b128 v[104:107], v237 offset:2176
	ds_read_b128 v[108:111], v237 offset:3264
	s_waitcnt lgkmcnt(0)
;   DI void operator()(const f32x16 (&acc)[2][4], int mbase, int nbase, int l32, int g) const {
; #pragma unroll
;     for (int nb = 0; nb < 2; ++nb)
; #pragma unroll
;       for (int mb = 0; mb < 4; ++mb) {
;         const size_t tok = mbase + 32 * mb + l32;
; #pragma unroll
;         for (int j = 0; j < 4; ++j) {
;           const int n = nbase + 32 * nb + 8 * j + 4 * g;
;           f32x4 r = *(const f32x4*)(R + tok * D + n);
;           r[0] += acc[nb][mb][4 * j]; r[1] += acc[nb][mb][4 * j + 1]; r[2] += acc[nb][mb][4 * j + 2]; r[3] += acc[nb][mb][4 * j + 3];
;           *(f32x4*)(O + tok * D + n) = r;
;         }
;       }
;   }
	s_waitcnt vmcnt(23)
	v_pk_add_f32 v[96:97], v[96:97], v[200:201]
	v_pk_add_f32 v[98:99], v[98:99], v[202:203]
	global_store_dwordx4 v238, v[96:99], s[100:101]
	s_add_u32 s100, s100, 0x8000
	s_addc_u32 s101, s101, 0
	s_waitcnt vmcnt(23)
	v_pk_add_f32 v[100:101], v[100:101], v[208:209]
	v_pk_add_f32 v[102:103], v[102:103], v[210:211]
	global_store_dwordx4 v238, v[100:103], s[100:101]
	s_add_u32 s100, s100, 0x8000
	s_addc_u32 s101, s101, 0
	s_waitcnt vmcnt(23)
	v_pk_add_f32 v[104:105], v[104:105], v[212:213]
	v_pk_add_f32 v[106:107], v[106:107], v[214:215]
	global_store_dwordx4 v238, v[104:107], s[100:101]
	s_add_u32 s100, s100, 0x8000
	s_addc_u32 s101, s101, 0
	s_waitcnt vmcnt(23)
	v_pk_add_f32 v[108:109], v[108:109], v[216:217]
	v_pk_add_f32 v[110:111], v[110:111], v[218:219]
	global_store_dwordx4 v238, v[108:111], s[100:101]
	s_add_u32 s100, s100, 0x8000
	s_addc_u32 s101, s101, 0
	global_load_dwordx4 v[200:203], v238, s[2:3]
	s_add_u32 s2, s2, 0x8000
	s_addc_u32 s3, s3, 0
	global_load_dwordx4 v[208:211], v238, s[2:3]
	s_add_u32 s2, s2, 0x8000
	s_addc_u32 s3, s3, 0
	global_load_dwordx4 v[212:215], v238, s[2:3]
	s_add_u32 s2, s2, 0x8000
	s_addc_u32 s3, s3, 0
	global_load_dwordx4 v[216:219], v238, s[2:3]
	s_add_u32 s2, s2, 0x8000
	s_addc_u32 s3, s3, 0
	ds_read_b128 v[32:35], v237 offset:4352
	ds_read_b128 v[36:39], v237 offset:5440
	ds_read_b128 v[40:43], v237 offset:6528
	ds_read_b128 v[44:47], v237 offset:7616
	s_waitcnt lgkmcnt(0)
	s_waitcnt vmcnt(27)
	v_pk_add_f32 v[32:33], v[32:33], v[220:221]
	v_pk_add_f32 v[34:35], v[34:35], v[222:223]
	global_store_dwordx4 v238, v[32:35], s[100:101]
	s_add_u32 s100, s100, 0x8000
	s_addc_u32 s101, s101, 0
	s_waitcnt vmcnt(27)
	v_pk_add_f32 v[36:37], v[36:37], v[224:225]
	v_pk_add_f32 v[38:39], v[38:39], v[226:227]
	global_store_dwordx4 v238, v[36:39], s[100:101]
	s_add_u32 s100, s100, 0x8000
	s_addc_u32 s101, s101, 0
	s_waitcnt vmcnt(27)
	v_pk_add_f32 v[40:41], v[40:41], v[228:229]
	v_pk_add_f32 v[42:43], v[42:43], v[230:231]
	global_store_dwordx4 v238, v[40:43], s[100:101]
	s_add_u32 s100, s100, 0x8000
	s_addc_u32 s101, s101, 0
	s_waitcnt vmcnt(27)
	v_pk_add_f32 v[44:45], v[44:45], v[232:233]
	v_pk_add_f32 v[46:47], v[46:47], v[234:235]
	global_store_dwordx4 v238, v[44:47], s[100:101]
	s_add_u32 s100, s100, 0x8000
	s_addc_u32 s101, s101, 0
	global_load_dwordx4 v[220:223], v238, s[2:3]
	s_add_u32 s2, s2, 0x8000
	s_addc_u32 s3, s3, 0
	global_load_dwordx4 v[224:227], v238, s[2:3]
	s_add_u32 s2, s2, 0x8000
	s_addc_u32 s3, s3, 0
	global_load_dwordx4 v[228:231], v238, s[2:3]
	s_add_u32 s2, s2, 0x8000
	s_addc_u32 s3, s3, 0
	global_load_dwordx4 v[232:235], v238, s[2:3]
	s_add_u32 s2, s2, 0x8000
	s_addc_u32 s3, s3, 0
	ds_write_b128 v236, v[80:83]
	ds_write_b128 v236, v[84:87] offset:32
	ds_write_b128 v236, v[88:91] offset:64
	ds_write_b128 v236, v[92:95] offset:96
	ds_write_b128 v236, v[16:19] offset:128
	ds_write_b128 v236, v[20:23] offset:160
	ds_write_b128 v236, v[24:27] offset:192
	ds_write_b128 v236, v[28:31] offset:224
	ds_read_b128 v[80:83], v237
	ds_read_b128 v[84:87], v237 offset:1088
	ds_read_b128 v[88:91], v237 offset:2176
	ds_read_b128 v[92:95], v237 offset:3264
	s_waitcnt lgkmcnt(0)
	s_waitcnt vmcnt(27)
	v_pk_add_f32 v[80:81], v[80:81], v[160:161]
	v_pk_add_f32 v[82:83], v[82:83], v[162:163]
	global_store_dwordx4 v238, v[80:83], s[100:101]
	s_add_u32 s100, s100, 0x8000
	s_addc_u32 s101, s101, 0
	s_waitcnt vmcnt(27)
	v_pk_add_f32 v[84:85], v[84:85], v[164:165]
	v_pk_add_f32 v[86:87], v[86:87], v[166:167]
	global_store_dwordx4 v238, v[84:87], s[100:101]
	s_add_u32 s100, s100, 0x8000
	s_addc_u32 s101, s101, 0
	s_waitcnt vmcnt(27)
	v_pk_add_f32 v[88:89], v[88:89], v[168:169]
	v_pk_add_f32 v[90:91], v[90:91], v[170:171]
	global_store_dwordx4 v238, v[88:91], s[100:101]
	s_add_u32 s100, s100, 0x8000
	s_addc_u32 s101, s101, 0
	s_waitcnt vmcnt(27)
;   DI void operator()(const f32x16 (&acc)[2][4], int mbase, int nbase, int l32, int g) const {
; #pragma unroll
;     for (int nb = 0; nb < 2; ++nb)
; #pragma unroll
;       for (int mb = 0; mb < 4; ++mb) {
;         const size_t tok = mbase + 32 * mb + l32;
; #pragma unroll
;         for (int j = 0; j < 4; ++j) {
;           const int n = nbase + 32 * nb + 8 * j + 4 * g;
;           f32x4 r = *(const f32x4*)(R + tok * D + n);
;           r[0] += acc[nb][mb][4 * j]; r[1] += acc[nb][mb][4 * j + 1]; r[2] += acc[nb][mb][4 * j + 2]; r[3] += acc[nb][mb][4 * j + 3];
;           *(f32x4*)(O + tok * D + n) = r;
;         }
;       }
;   }
	v_pk_add_f32 v[92:93], v[92:93], v[172:173]
	v_pk_add_f32 v[94:95], v[94:95], v[174:175]
	global_store_dwordx4 v238, v[92:95], s[100:101]
	s_add_u32 s100, s100, 0x8000
	s_addc_u32 s101, s101, 0
	ds_read_b128 v[16:19], v237 offset:4352
	ds_read_b128 v[20:23], v237 offset:5440
	ds_read_b128 v[24:27], v237 offset:6528
	ds_read_b128 v[28:31], v237 offset:7616
	s_waitcnt lgkmcnt(0)
	s_waitcnt vmcnt(23)
	v_pk_add_f32 v[16:17], v[16:17], v[176:177]
	v_pk_add_f32 v[18:19], v[18:19], v[178:179]
	global_store_dwordx4 v238, v[16:19], s[100:101]
	s_add_u32 s100, s100, 0x8000
	s_addc_u32 s101, s101, 0
	s_waitcnt vmcnt(23)
	v_pk_add_f32 v[20:21], v[20:21], v[180:181]
	v_pk_add_f32 v[22:23], v[22:23], v[182:183]
	global_store_dwordx4 v238, v[20:23], s[100:101]
	s_add_u32 s100, s100, 0x8000
	s_addc_u32 s101, s101, 0
	s_waitcnt vmcnt(23)
	v_pk_add_f32 v[24:25], v[24:25], v[186:187]
	v_pk_add_f32 v[26:27], v[26:27], v[188:189]
	global_store_dwordx4 v238, v[24:27], s[100:101]
	s_add_u32 s100, s100, 0x8000
	s_addc_u32 s101, s101, 0
	s_waitcnt vmcnt(23)
	v_pk_add_f32 v[28:29], v[28:29], v[192:193]
	v_pk_add_f32 v[30:31], v[30:31], v[194:195]
	global_store_dwordx4 v238, v[28:31], s[100:101]
	s_add_u32 s100, s100, 0x8000
	s_addc_u32 s101, s101, 0
	ds_write_b128 v236, v[64:67]
	ds_write_b128 v236, v[68:71] offset:32
	ds_write_b128 v236, v[72:75] offset:64
	ds_write_b128 v236, v[76:79] offset:96
	ds_write_b128 v236, v[0:3] offset:128
	ds_write_b128 v236, v[4:7] offset:160
	ds_write_b128 v236, v[8:11] offset:192
	ds_write_b128 v236, v[12:15] offset:224
	ds_read_b128 v[64:67], v237
	ds_read_b128 v[68:71], v237 offset:1088
	ds_read_b128 v[72:75], v237 offset:2176
	ds_read_b128 v[76:79], v237 offset:3264
	s_waitcnt lgkmcnt(0)
	s_waitcnt vmcnt(19)
	v_pk_add_f32 v[64:65], v[64:65], v[200:201]
	v_pk_add_f32 v[66:67], v[66:67], v[202:203]
	global_store_dwordx4 v238, v[64:67], s[100:101]
	s_add_u32 s100, s100, 0x8000
	s_addc_u32 s101, s101, 0
	s_waitcnt vmcnt(19)
	v_pk_add_f32 v[68:69], v[68:69], v[208:209]
	v_pk_add_f32 v[70:71], v[70:71], v[210:211]
	global_store_dwordx4 v238, v[68:71], s[100:101]
	s_add_u32 s100, s100, 0x8000
	s_addc_u32 s101, s101, 0
	s_waitcnt vmcnt(19)
	v_pk_add_f32 v[72:73], v[72:73], v[212:213]
	v_pk_add_f32 v[74:75], v[74:75], v[214:215]
	global_store_dwordx4 v238, v[72:75], s[100:101]
	s_add_u32 s100, s100, 0x8000
	s_addc_u32 s101, s101, 0
	s_waitcnt vmcnt(19)
	v_pk_add_f32 v[76:77], v[76:77], v[216:217]
	v_pk_add_f32 v[78:79], v[78:79], v[218:219]
	global_store_dwordx4 v238, v[76:79], s[100:101]
	s_add_u32 s100, s100, 0x8000
	s_addc_u32 s101, s101, 0
	ds_read_b128 v[0:3], v237 offset:4352
	ds_read_b128 v[4:7], v237 offset:5440
	ds_read_b128 v[8:11], v237 offset:6528
	ds_read_b128 v[12:15], v237 offset:7616
	s_waitcnt lgkmcnt(0)
	s_waitcnt vmcnt(15)
	v_pk_add_f32 v[0:1], v[0:1], v[220:221]
	v_pk_add_f32 v[2:3], v[2:3], v[222:223]
	global_store_dwordx4 v238, v[0:3], s[100:101]
	s_add_u32 s100, s100, 0x8000
	s_addc_u32 s101, s101, 0
	s_waitcnt vmcnt(15)
	v_pk_add_f32 v[4:5], v[4:5], v[224:225]
	v_pk_add_f32 v[6:7], v[6:7], v[226:227]
	global_store_dwordx4 v238, v[4:7], s[100:101]
	s_add_u32 s100, s100, 0x8000
	s_addc_u32 s101, s101, 0
	s_waitcnt vmcnt(15)
	v_pk_add_f32 v[8:9], v[8:9], v[228:229]
	v_pk_add_f32 v[10:11], v[10:11], v[230:231]
	global_store_dwordx4 v238, v[8:11], s[100:101]
	s_add_u32 s100, s100, 0x8000
	s_addc_u32 s101, s101, 0
	s_waitcnt vmcnt(15)
	v_pk_add_f32 v[12:13], v[12:13], v[232:233]
	v_pk_add_f32 v[14:15], v[14:15], v[234:235]
	global_store_dwordx4 v238, v[12:15], s[100:101]
	s_add_u32 s100, s100, 0x8000
	s_addc_u32 s101, s101, 0
	s_and_b64 vcc, exec, s[6:7]
	s_cbranch_vccz .LBB0_767

;   DI void operator()(const f32x16 (&acc)[2][4], int mbase, int nbase, int l32, int g) const {
; #pragma unroll
;     for (int nb = 0; nb < 2; ++nb)
; #pragma unroll
;       for (int mb = 0; mb < 4; ++mb) {
;         const size_t tok = mbase + 32 * mb + l32;
; #pragma unroll
;         for (int j = 0; j < 4; ++j) {
;           const int n = nbase + 32 * nb + 8 * j + 4 * g;
;           f32x4 r = *(const f32x4*)(R + tok * D + n);
;           r[0] += acc[nb][mb][4 * j]; r[1] += acc[nb][mb][4 * j + 1]; r[2] += acc[nb][mb][4 * j + 2]; r[3] += acc[nb][mb][4 * j + 3];
;           *(f32x4*)(O + tok * D + n) = r;
;         }
;       }
;   }
; DI void phase_gemm_out(const Params& p, char* smem, const bf16_t* Wt, const float* R, float* O) {
;     ...
;     WAVE_GEOM;
;     f32x16 acc[2][4];
;     gemm_core<false>(tl, nx, has_next, has_next, pre, ra, rb, smem, acc);
;     const float* Rq = R; asm volatile("" : "+s"(Rq));
;     EpiResid e{Rq, O};
;     e(acc, mt * 256 + wm_ * 128, nt * 256 + wn_ * 64, l32_, g_);
.LBB0_1632:
	s_lshr_b32 s98, s9, 6
	s_and_b32 s10, s9, 0xc0
	s_ashr_i32 s9, s9, 1
	s_and_b32 s9, s9, 0xffffff80
	s_add_i32 s9, s9, s36
	s_mul_i32 s98, s98, 0x2200
	s_add_i32 s98, s98, 0x12010
	s_or_b32 s99, s10, s8
	s_mov_b64 s[2:3], s[20:21]
	s_mov_b64 s[100:101], s[20:21]
	s_add_i32 s18, s18, s19
	s_add_i32 s24, s24, s25
	s_mov_b64 s[10:11], -1
	s_barrier
	v_and_b32_e32 v239, 31, v190
	v_bfe_u32 v240, v190, 5, 1
	v_mul_u32_u24_e32 v236, 0x110, v239
	v_lshl_add_u32 v236, v240, 4, v236
	v_add_u32_e32 v236, s98, v236
	v_and_b32_e32 v239, 15, v190
	v_bfe_u32 v240, v190, 4, 2
	v_mul_u32_u24_e32 v237, 0x110, v240
	v_lshl_add_u32 v237, v239, 4, v237
	v_add_u32_e32 v237, s98, v237
	v_add_u32_e32 v238, s9, v240
	v_lshlrev_b32_e32 v238, 13, v238
	v_lshl_add_u32 v240, v239, 2, s99
	v_lshl_add_u32 v238, v240, 2, v238
	global_load_dwordx4 v[160:163], v238, s[2:3]
	s_add_u32 s2, s2, 0x8000
	s_addc_u32 s3, s3, 0
	global_load_dwordx4 v[164:167], v238, s[2:3]
	s_add_u32 s2, s2, 0x8000
	s_addc_u32 s3, s3, 0
	global_load_dwordx4 v[168:171], v238, s[2:3]
	s_add_u32 s2, s2, 0x8000
	s_addc_u32 s3, s3, 0
	global_load_dwordx4 v[172:175], v238, s[2:3]
	s_add_u32 s2, s2, 0x8000
	s_addc_u32 s3, s3, 0
	global_load_dwordx4 v[176:179], v238, s[2:3]
	s_add_u32 s2, s2, 0x8000
	s_addc_u32 s3, s3, 0
	global_load_dwordx4 v[180:183], v238, s[2:3]
	s_add_u32 s2, s2, 0x8000
	s_addc_u32 s3, s3, 0
	global_load_dwordx4 v[186:189], v238, s[2:3]
	s_add_u32 s2, s2, 0x8000
	s_addc_u32 s3, s3, 0
	global_load_dwordx4 v[192:195], v238, s[2:3]
	s_add_u32 s2, s2, 0x8000
	s_addc_u32 s3, s3, 0
	global_load_dwordx4 v[200:203], v238, s[2:3]
	s_add_u32 s2, s2, 0x8000
	s_addc_u32 s3, s3, 0
	global_load_dwordx4 v[208:211], v238, s[2:3]
	s_add_u32 s2, s2, 0x8000
	s_addc_u32 s3, s3, 0
	global_load_dwordx4 v[212:215], v238, s[2:3]
	s_add_u32 s2, s2, 0x8000
	s_addc_u32 s3, s3, 0
	global_load_dwordx4 v[216:219], v238, s[2:3]
	s_add_u32 s2, s2, 0x8000
	s_addc_u32 s3, s3, 0
	global_load_dwordx4 v[220:223], v238, s[2:3]
	s_add_u32 s2, s2, 0x8000
	s_addc_u32 s3, s3, 0
	global_load_dwordx4 v[224:227], v238, s[2:3]
	s_add_u32 s2, s2, 0x8000
	s_addc_u32 s3, s3, 0
	global_load_dwordx4 v[228:231], v238, s[2:3]
	s_add_u32 s2, s2, 0x8000
	s_addc_u32 s3, s3, 0
	global_load_dwordx4 v[232:235], v238, s[2:3]
	s_add_u32 s2, s2, 0x8000
	s_addc_u32 s3, s3, 0
	ds_write_b128 v236, v[112:115]
	ds_write_b128 v236, v[116:119] offset:32
	ds_write_b128 v236, v[120:123] offset:64
	ds_write_b128 v236, v[124:127] offset:96
	ds_write_b128 v236, v[48:51] offset:128
	ds_write_b128 v236, v[52:55] offset:160
	ds_write_b128 v236, v[56:59] offset:192
	ds_write_b128 v236, v[60:63] offset:224
	ds_read_b128 v[112:115], v237
	ds_read_b128 v[116:119], v237 offset:1088
	ds_read_b128 v[120:123], v237 offset:2176
	ds_read_b128 v[124:127], v237 offset:3264
	s_waitcnt lgkmcnt(0)
	s_waitcnt vmcnt(15)
	v_pk_add_f32 v[112:113], v[112:113], v[160:161]
	v_pk_add_f32 v[114:115], v[114:115], v[162:163]
	global_store_dwordx4 v238, v[112:115], s[100:101]
	s_add_u32 s100, s100, 0x8000
	s_addc_u32 s101, s101, 0
	s_waitcnt vmcnt(15)
	v_pk_add_f32 v[116:117], v[116:117], v[164:165]
	v_pk_add_f32 v[118:119], v[118:119], v[166:167]
	global_store_dwordx4 v238, v[116:119], s[100:101]
	s_add_u32 s100, s100, 0x8000
	s_addc_u32 s101, s101, 0
	s_waitcnt vmcnt(15)
	v_pk_add_f32 v[120:121], v[120:121], v[168:169]
	v_pk_add_f32 v[122:123], v[122:123], v[170:171]
	global_store_dwordx4 v238, v[120:123], s[100:101]
	s_add_u32 s100, s100, 0x8000
	s_addc_u32 s101, s101, 0
	s_waitcnt vmcnt(15)
	v_pk_add_f32 v[124:125], v[124:125], v[172:173]
	v_pk_add_f32 v[126:127], v[126:127], v[174:175]
	global_store_dwordx4 v238, v[124:127], s[100:101]
	s_add_u32 s100, s100, 0x8000
	s_addc_u32 s101, s101, 0
	global_load_dwordx4 v[160:163], v238, s[2:3]
	s_add_u32 s2, s2, 0x8000
	s_addc_u32 s3, s3, 0
	global_load_dwordx4 v[164:167], v238, s[2:3]
	s_add_u32 s2, s2, 0x8000
	s_addc_u32 s3, s3, 0
	global_load_dwordx4 v[168:171], v238, s[2:3]
	s_add_u32 s2, s2, 0x8000
	s_addc_u32 s3, s3, 0
	global_load_dwordx4 v[172:175], v238, s[2:3]
	s_add_u32 s2, s2, 0x8000
	s_addc_u32 s3, s3, 0
	ds_read_b128 v[48:51], v237 offset:4352
	ds_read_b128 v[52:55], v237 offset:5440
	ds_read_b128 v[56:59], v237 offset:6528
	ds_read_b128 v[60:63], v237 offset:7616
	s_waitcnt lgkmcnt(0)
	s_waitcnt vmcnt(19)
	v_pk_add_f32 v[48:49], v[48:49], v[176:177]
	v_pk_add_f32 v[50:51], v[50:51], v[178:179]
	global_store_dwordx4 v238, v[48:51], s[100:101]
	s_add_u32 s100, s100, 0x8000
	s_addc_u32 s101, s101, 0
	s_waitcnt vmcnt(19)
	v_pk_add_f32 v[52:53], v[52:53], v[180:181]
	v_pk_add_f32 v[54:55], v[54:55], v[182:183]
	global_store_dwordx4 v238, v[52:55], s[100:101]
	s_add_u32 s100, s100, 0x8000
	s_addc_u32 s101, s101, 0
	s_waitcnt vmcnt(19)
	v_pk_add_f32 v[56:57], v[56:57], v[186:187]
	v_pk_add_f32 v[58:59], v[58:59], v[188:189]
	global_store_dwordx4 v238, v[56:59], s[100:101]
	s_add_u32 s100, s100, 0x8000
	s_addc_u32 s101, s101, 0
	s_waitcnt vmcnt(19)
	v_pk_add_f32 v[60:61], v[60:61], v[192:193]
	v_pk_add_f32 v[62:63], v[62:63], v[194:195]
	global_store_dwordx4 v238, v[60:63], s[100:101]
	s_add_u32 s100, s100, 0x8000
	s_addc_u32 s101, s101, 0
	global_load_dwordx4 v[176:179], v238, s[2:3]
	s_add_u32 s2, s2, 0x8000
	s_addc_u32 s3, s3, 0
	global_load_dwordx4 v[180:183], v238, s[2:3]
	s_add_u32 s2, s2, 0x8000
	s_addc_u32 s3, s3, 0
	global_load_dwordx4 v[186:189], v238, s[2:3]
	s_add_u32 s2, s2, 0x8000
	s_addc_u32 s3, s3, 0
	global_load_dwordx4 v[192:195], v238, s[2:3]
	s_add_u32 s2, s2, 0x8000
	s_addc_u32 s3, s3, 0
	ds_write_b128 v236, v[96:99]
	ds_write_b128 v236, v[100:103] offset:32
	ds_write_b128 v236, v[104:107] offset:64
	ds_write_b128 v236, v[108:111] offset:96
	ds_write_b128 v236, v[32:35] offset:128
	ds_write_b128 v236, v[36:39] offset:160
	ds_write_b128 v236, v[40:43] offset:192
	ds_write_b128 v236, v[44:47] offset:224
	ds_read_b128 v[96:99], v237
	ds_read_b128 v[100:103], v237 offset:1088
	ds_read_b128 v[104:107], v237 offset:2176
	ds_read_b128 v[108:111], v237 offset:3264
	s_waitcnt lgkmcnt(0)
;   DI void operator()(const f32x16 (&acc)[2][4], int mbase, int nbase, int l32, int g) const {
; #pragma unroll
;     for (int nb = 0; nb < 2; ++nb)
; #pragma unroll
;       for (int mb = 0; mb < 4; ++mb) {
;         const size_t tok = mbase + 32 * mb + l32;
; #pragma unroll
;         for (int j = 0; j < 4; ++j) {
;           const int n = nbase + 32 * nb + 8 * j + 4 * g;
;           f32x4 r = *(const f32x4*)(R + tok * D + n);
;           r[0] += acc[nb][mb][4 * j]; r[1] += acc[nb][mb][4 * j + 1]; r[2] += acc[nb][mb][4 * j + 2]; r[3] += acc[nb][mb][4 * j + 3];
;           *(f32x4*)(O + tok * D + n) = r;
;         }
;       }
;   }
	s_waitcnt vmcnt(23)
	v_pk_add_f32 v[96:97], v[96:97], v[200:201]
	v_pk_add_f32 v[98:99], v[98:99], v[202:203]
	global_store_dwordx4 v238, v[96:99], s[100:101]
	s_add_u32 s100, s100, 0x8000
	s_addc_u32 s101, s101, 0
	s_waitcnt vmcnt(23)
	v_pk_add_f32 v[100:101], v[100:101], v[208:209]
	v_pk_add_f32 v[102:103], v[102:103], v[210:211]
	global_store_dwordx4 v238, v[100:103], s[100:101]
	s_add_u32 s100, s100, 0x8000
	s_addc_u32 s101, s101, 0
	s_waitcnt vmcnt(23)
	v_pk_add_f32 v[104:105], v[104:105], v[212:213]
	v_pk_add_f32 v[106:107], v[106:107], v[214:215]
	global_store_dwordx4 v238, v[104:107], s[100:101]
	s_add_u32 s100, s100, 0x8000
	s_addc_u32 s101, s101, 0
	s_waitcnt vmcnt(23)
	v_pk_add_f32 v[108:109], v[108:109], v[216:217]
	v_pk_add_f32 v[110:111], v[110:111], v[218:219]
	global_store_dwordx4 v238, v[108:111], s[100:101]
	s_add_u32 s100, s100, 0x8000
	s_addc_u32 s101, s101, 0
	global_load_dwordx4 v[200:203], v238, s[2:3]
	s_add_u32 s2, s2, 0x8000
	s_addc_u32 s3, s3, 0
	global_load_dwordx4 v[208:211], v238, s[2:3]
	s_add_u32 s2, s2, 0x8000
	s_addc_u32 s3, s3, 0
	global_load_dwordx4 v[212:215], v238, s[2:3]
	s_add_u32 s2, s2, 0x8000
	s_addc_u32 s3, s3, 0
	global_load_dwordx4 v[216:219], v238, s[2:3]
	s_add_u32 s2, s2, 0x8000
	s_addc_u32 s3, s3, 0
	ds_read_b128 v[32:35], v237 offset:4352
	ds_read_b128 v[36:39], v237 offset:5440
	ds_read_b128 v[40:43], v237 offset:6528
	ds_read_b128 v[44:47], v237 offset:7616
	s_waitcnt lgkmcnt(0)
	s_waitcnt vmcnt(27)
	v_pk_add_f32 v[32:33], v[32:33], v[220:221]
	v_pk_add_f32 v[34:35], v[34:35], v[222:223]
	global_store_dwordx4 v238, v[32:35], s[100:101]
	s_add_u32 s100, s100, 0x8000
	s_addc_u32 s101, s101, 0
	s_waitcnt vmcnt(27)
	v_pk_add_f32 v[36:37], v[36:37], v[224:225]
	v_pk_add_f32 v[38:39], v[38:39], v[226:227]
	global_store_dwordx4 v238, v[36:39], s[100:101]
	s_add_u32 s100, s100, 0x8000
	s_addc_u32 s101, s101, 0
	s_waitcnt vmcnt(27)
	v_pk_add_f32 v[40:41], v[40:41], v[228:229]
	v_pk_add_f32 v[42:43], v[42:43], v[230:231]
	global_store_dwordx4 v238, v[40:43], s[100:101]
	s_add_u32 s100, s100, 0x8000
	s_addc_u32 s101, s101, 0
	s_waitcnt vmcnt(27)
	v_pk_add_f32 v[44:45], v[44:45], v[232:233]
	v_pk_add_f32 v[46:47], v[46:47], v[234:235]
	global_store_dwordx4 v238, v[44:47], s[100:101]
	s_add_u32 s100, s100, 0x8000
	s_addc_u32 s101, s101, 0
	global_load_dwordx4 v[220:223], v238, s[2:3]
	s_add_u32 s2, s2, 0x8000
	s_addc_u32 s3, s3, 0
	global_load_dwordx4 v[224:227], v238, s[2:3]
	s_add_u32 s2, s2, 0x8000
	s_addc_u32 s3, s3, 0
	global_load_dwordx4 v[228:231], v238, s[2:3]
	s_add_u32 s2, s2, 0x8000
	s_addc_u32 s3, s3, 0
	global_load_dwordx4 v[232:235], v238, s[2:3]
	s_add_u32 s2, s2, 0x8000
	s_addc_u32 s3, s3, 0
	ds_write_b128 v236, v[80:83]
	ds_write_b128 v236, v[84:87] offset:32
	ds_write_b128 v236, v[88:91] offset:64
	ds_write_b128 v236, v[92:95] offset:96
	ds_write_b128 v236, v[16:19] offset:128
	ds_write_b128 v236, v[20:23] offset:160
	ds_write_b128 v236, v[24:27] offset:192
	ds_write_b128 v236, v[28:31] offset:224
	ds_read_b128 v[80:83], v237
	ds_read_b128 v[84:87], v237 offset:1088
	ds_read_b128 v[88:91], v237 offset:2176
	ds_read_b128 v[92:95], v237 offset:3264
	s_waitcnt lgkmcnt(0)
	s_waitcnt vmcnt(27)
	v_pk_add_f32 v[80:81], v[80:81], v[160:161]
	v_pk_add_f32 v[82:83], v[82:83], v[162:163]
	global_store_dwordx4 v238, v[80:83], s[100:101]
	s_add_u32 s100, s100, 0x8000
	s_addc_u32 s101, s101, 0
	s_waitcnt vmcnt(27)
	v_pk_add_f32 v[84:85], v[84:85], v[164:165]
	v_pk_add_f32 v[86:87], v[86:87], v[166:167]
	global_store_dwordx4 v238, v[84:87], s[100:101]
	s_add_u32 s100, s100, 0x8000
	s_addc_u32 s101, s101, 0
	s_waitcnt vmcnt(27)
	v_pk_add_f32 v[88:89], v[88:89], v[168:169]
	v_pk_add_f32 v[90:91], v[90:91], v[170:171]
	global_store_dwordx4 v238, v[88:91], s[100:101]
	s_add_u32 s100, s100, 0x8000
	s_addc_u32 s101, s101, 0
	s_waitcnt vmcnt(27)
;   DI void operator()(const f32x16 (&acc)[2][4], int mbase, int nbase, int l32, int g) const {
; #pragma unroll
;     for (int nb = 0; nb < 2; ++nb)
; #pragma unroll
;       for (int mb = 0; mb < 4; ++mb) {
;         const size_t tok = mbase + 32 * mb + l32;
; #pragma unroll
;         for (int j = 0; j < 4; ++j) {
;           const int n = nbase + 32 * nb + 8 * j + 4 * g;
;           f32x4 r = *(const f32x4*)(R + tok * D + n);
;           r[0] += acc[nb][mb][4 * j]; r[1] += acc[nb][mb][4 * j + 1]; r[2] += acc[nb][mb][4 * j + 2]; r[3] += acc[nb][mb][4 * j + 3];
;           *(f32x4*)(O + tok * D + n) = r;
;         }
;       }
;   }
	v_pk_add_f32 v[92:93], v[92:93], v[172:173]
	v_pk_add_f32 v[94:95], v[94:95], v[174:175]
	global_store_dwordx4 v238, v[92:95], s[100:101]
	s_add_u32 s100, s100, 0x8000
	s_addc_u32 s101, s101, 0
	ds_read_b128 v[16:19], v237 offset:4352
	ds_read_b128 v[20:23], v237 offset:5440
	ds_read_b128 v[24:27], v237 offset:6528
	ds_read_b128 v[28:31], v237 offset:7616
	s_waitcnt lgkmcnt(0)
	s_waitcnt vmcnt(23)
	v_pk_add_f32 v[16:17], v[16:17], v[176:177]
	v_pk_add_f32 v[18:19], v[18:19], v[178:179]
	global_store_dwordx4 v238, v[16:19], s[100:101]
	s_add_u32 s100, s100, 0x8000
	s_addc_u32 s101, s101, 0
	s_waitcnt vmcnt(23)
	v_pk_add_f32 v[20:21], v[20:21], v[180:181]
	v_pk_add_f32 v[22:23], v[22:23], v[182:183]
	global_store_dwordx4 v238, v[20:23], s[100:101]
	s_add_u32 s100, s100, 0x8000
	s_addc_u32 s101, s101, 0
	s_waitcnt vmcnt(23)
	v_pk_add_f32 v[24:25], v[24:25], v[186:187]
	v_pk_add_f32 v[26:27], v[26:27], v[188:189]
	global_store_dwordx4 v238, v[24:27], s[100:101]
	s_add_u32 s100, s100, 0x8000
	s_addc_u32 s101, s101, 0
	s_waitcnt vmcnt(23)
	v_pk_add_f32 v[28:29], v[28:29], v[192:193]
	v_pk_add_f32 v[30:31], v[30:31], v[194:195]
	global_store_dwordx4 v238, v[28:31], s[100:101]
	s_add_u32 s100, s100, 0x8000
	s_addc_u32 s101, s101, 0
	ds_write_b128 v236, v[64:67]
	ds_write_b128 v236, v[68:71] offset:32
	ds_write_b128 v236, v[72:75] offset:64
	ds_write_b128 v236, v[76:79] offset:96
	ds_write_b128 v236, v[0:3] offset:128
	ds_write_b128 v236, v[4:7] offset:160
	ds_write_b128 v236, v[8:11] offset:192
	ds_write_b128 v236, v[12:15] offset:224
	ds_read_b128 v[64:67], v237
	ds_read_b128 v[68:71], v237 offset:1088
	ds_read_b128 v[72:75], v237 offset:2176
	ds_read_b128 v[76:79], v237 offset:3264
	s_waitcnt lgkmcnt(0)
	s_waitcnt vmcnt(19)
	v_pk_add_f32 v[64:65], v[64:65], v[200:201]
	v_pk_add_f32 v[66:67], v[66:67], v[202:203]
	global_store_dwordx4 v238, v[64:67], s[100:101]
	s_add_u32 s100, s100, 0x8000
	s_addc_u32 s101, s101, 0
	s_waitcnt vmcnt(19)
	v_pk_add_f32 v[68:69], v[68:69], v[208:209]
	v_pk_add_f32 v[70:71], v[70:71], v[210:211]
	global_store_dwordx4 v238, v[68:71], s[100:101]
	s_add_u32 s100, s100, 0x8000
	s_addc_u32 s101, s101, 0
	s_waitcnt vmcnt(19)
	v_pk_add_f32 v[72:73], v[72:73], v[212:213]
	v_pk_add_f32 v[74:75], v[74:75], v[214:215]
	global_store_dwordx4 v238, v[72:75], s[100:101]
	s_add_u32 s100, s100, 0x8000
	s_addc_u32 s101, s101, 0
	s_waitcnt vmcnt(19)
	v_pk_add_f32 v[76:77], v[76:77], v[216:217]
	v_pk_add_f32 v[78:79], v[78:79], v[218:219]
	global_store_dwordx4 v238, v[76:79], s[100:101]
	s_add_u32 s100, s100, 0x8000
	s_addc_u32 s101, s101, 0
	ds_read_b128 v[0:3], v237 offset:4352
	ds_read_b128 v[4:7], v237 offset:5440
	ds_read_b128 v[8:11], v237 offset:6528
	ds_read_b128 v[12:15], v237 offset:7616
	s_waitcnt lgkmcnt(0)
	s_waitcnt vmcnt(15)
	v_pk_add_f32 v[0:1], v[0:1], v[220:221]
	v_pk_add_f32 v[2:3], v[2:3], v[222:223]
	global_store_dwordx4 v238, v[0:3], s[100:101]
	s_add_u32 s100, s100, 0x8000
	s_addc_u32 s101, s101, 0
	s_waitcnt vmcnt(15)
	v_pk_add_f32 v[4:5], v[4:5], v[224:225]
	v_pk_add_f32 v[6:7], v[6:7], v[226:227]
	global_store_dwordx4 v238, v[4:7], s[100:101]
	s_add_u32 s100, s100, 0x8000
	s_addc_u32 s101, s101, 0
	s_waitcnt vmcnt(15)
	v_pk_add_f32 v[8:9], v[8:9], v[228:229]
	v_pk_add_f32 v[10:11], v[10:11], v[230:231]
	global_store_dwordx4 v238, v[8:11], s[100:101]
	s_add_u32 s100, s100, 0x8000
	s_addc_u32 s101, s101, 0
	s_waitcnt vmcnt(15)
	v_pk_add_f32 v[12:13], v[12:13], v[232:233]
	v_pk_add_f32 v[14:15], v[14:15], v[234:235]
	global_store_dwordx4 v238, v[12:15], s[100:101]
	s_add_u32 s100, s100, 0x8000
	s_addc_u32 s101, s101, 0
	s_and_b64 vcc, exec, s[4:5]
	s_cbranch_vccz .LBB0_1655

; __global__ void __launch_bounds__(NTH, 2) mega_kernel(Params p) {
;   extern __shared__ __attribute__((aligned(16))) char smem[];
	.amdhsa_kernel _Z11mega_kernel6Params
		.amdhsa_group_segment_fixed_size 16
		.amdhsa_private_segment_fixed_size 0
		.amdhsa_kernarg_size 464
		.amdhsa_user_sgpr_count 2
		.amdhsa_user_sgpr_dispatch_ptr 0
		.amdhsa_user_sgpr_queue_ptr 0
		.amdhsa_user_sgpr_kernarg_segment_ptr 1
		.amdhsa_user_sgpr_dispatch_id 0
		.amdhsa_user_sgpr_kernarg_preload_length 0
		.amdhsa_user_sgpr_kernarg_preload_offset 0
		.amdhsa_user_sgpr_private_segment_size 0
		.amdhsa_uses_dynamic_stack 0
		.amdhsa_enable_private_segment 0
		.amdhsa_system_sgpr_workgroup_id_x 1
		.amdhsa_system_sgpr_workgroup_id_y 0
		.amdhsa_system_sgpr_workgroup_id_z 0
		.amdhsa_system_sgpr_workgroup_info 0
		.amdhsa_system_vgpr_workitem_id 2
		.amdhsa_next_free_vgpr 253
		.amdhsa_next_free_sgpr 102
		.amdhsa_accum_offset 256
		.amdhsa_reserve_vcc 1
		.amdhsa_float_round_mode_32 0
		.amdhsa_float_round_mode_16_64 0
		.amdhsa_float_denorm_mode_32 3
		.amdhsa_float_denorm_mode_16_64 3
		.amdhsa_dx10_clamp 1
		.amdhsa_ieee_mode 1
		.amdhsa_fp16_overflow 0
		.amdhsa_tg_split 0
		.amdhsa_exception_fp_ieee_invalid_op 0
		.amdhsa_exception_fp_denorm_src 0
		.amdhsa_exception_fp_ieee_div_zero 0
		.amdhsa_exception_fp_ieee_overflow 0
		.amdhsa_exception_fp_ieee_underflow 0
		.amdhsa_exception_fp_ieee_inexact 0
		.amdhsa_exception_int_div_zero 0
	.end_amdhsa_kernel

; __global__ void __launch_bounds__(NTH, 2) mega_kernel(Params p) {
;   extern __shared__ __attribute__((aligned(16))) char smem[];
amdhsa.kernels:
  - .agpr_count:     0
    .args:
      - .offset:         0
        .size:           208
        .value_kind:     by_value
      - .offset:         208
        .size:           4
        .value_kind:     hidden_block_count_x
      - .offset:         212
        .size:           4
        .value_kind:     hidden_block_count_y
      - .offset:         216
        .size:           4
        .value_kind:     hidden_block_count_z
      - .offset:         220
        .size:           2
        .value_kind:     hidden_group_size_x
      - .offset:         222
        .size:           2
        .value_kind:     hidden_group_size_y
      - .offset:         224
        .size:           2
        .value_kind:     hidden_group_size_z
      - .offset:         226
        .size:           2
        .value_kind:     hidden_remainder_x
      - .offset:         228
        .size:           2
        .value_kind:     hidden_remainder_y
      - .offset:         230
        .size:           2
        .value_kind:     hidden_remainder_z
      - .offset:         248
        .size:           8
        .value_kind:     hidden_global_offset_x
      - .offset:         256
        .size:           8
        .value_kind:     hidden_global_offset_y
      - .offset:         264
        .size:           8
        .value_kind:     hidden_global_offset_z
      - .offset:         272
        .size:           2
        .value_kind:     hidden_grid_dims
      - .offset:         296
        .size:           8
        .value_kind:     hidden_multigrid_sync_arg
      - .offset:         328
        .size:           4
        .value_kind:     hidden_dynamic_lds_size
    .group_segment_fixed_size: 16
    .kernarg_segment_align: 8
    .kernarg_segment_size: 464
    .language:       OpenCL C
    .language_version:
      - 2
      - 0
    .max_flat_workgroup_size: 512
    .name:           _Z11mega_kernel6Params
    .private_segment_fixed_size: 0
    .sgpr_count:     108
    .sgpr_spill_count: 182
    .symbol:         _Z11mega_kernel6Params.kd
    .uniform_work_group_size: 1
    .uses_dynamic_stack: false
    .vgpr_count:     253
    .vgpr_spill_count: 0
    .wavefront_size: 64
